# FFN-down instances (gd, ge, gf; one block per CU): whole next-stage DMA issued right after the stage barrier; FFN-up and w_in keep 4 early pieces
# baseline (speedup 1.0000x reference)
; template <int EPI, int MI>
; DI void gemm_tile(const GemmDesc& g, int tm, int tn, char* smem) {
;     ...
;   const int tid = get_tid(), lane = tid & 63, wave = tid >> 6, r = lane & 31, hh = lane >> 5;
;   const int wm = wave >> 1, wn = wave & 1;
;   const int m0 = tm * BM, n0 = tn * 128;
;   const int nk = g.K >> 6;
;   f32x16 acc[MI][2];
; #pragma unroll
;   for (int a = 0; a < MI; ++a)
; #pragma unroll
;     for (int b = 0; b < 2; ++b)
; #pragma unroll
;       for (int i = 0; i < 16; ++i) acc[a][b][i] = 0.f;
;   const int srow = tid >> 3;
;   const int schunk = (tid & 7) ^ ((srow & 7) ^ ((srow >> 3) & 3));
;     ...
;   const int rowA = wm * (32 * MI) + r, rowB = wn * 64 + r;
;   const int hk = hh ^ ((r & 7) ^ ((r >> 3) & 3));
;     ...
;   G_GLDS(0, 0);
;   asm volatile("s_waitcnt vmcnt(0)" ::: "memory");
;   __syncthreads();
; template <int EPI, int MI>
; DI void gemm_phase(const GemmDesc& g, char* smem, int vb, int nvb) {
;     ...
;   for (int q = start; q < local; q += step) {
;     const int mg = q / per;
;     const int rem = q - mg * per;
;     const int tn = rem / PM;
;     const int tm = mbase + mg * PM + (rem - tn * PM);
.LBB0_1478:
	s_abs_i32 s0, s44
	s_mul_hi_u32 s1, s0, s42
	s_mul_i32 s4, s1, s38
	s_sub_i32 s0, s0, s4
	s_ashr_i32 s18, s44, 31
	s_add_i32 s4, s1, 1
	s_sub_i32 s5, s0, s38
	s_cmp_ge_u32 s0, s38
	s_cselect_b32 s1, s4, s1
	s_cselect_b32 s0, s5, s0
	s_add_i32 s4, s1, 1
	s_cmp_ge_u32 s0, s38
	s_cselect_b32 s0, s4, s1
	s_xor_b32 s19, s0, s18
	s_sub_i32 s0, s19, s18
	s_mul_i32 s1, s0, s38
	s_sub_i32 s1, s44, s1
	s_abs_i32 s4, s1
	s_mul_hi_u32 s5, s4, s16
	s_mul_i32 s45, s5, s15
	s_sub_i32 s4, s4, s45
	s_ashr_i32 s46, s1, 31
	s_add_i32 s45, s5, 1
	s_sub_i32 s47, s4, s15
	s_cmp_ge_u32 s4, s15
	s_cselect_b32 s5, s45, s5
	s_cselect_b32 s4, s47, s4
	s_add_i32 s45, s5, 1
	s_cmp_ge_u32 s4, s15
	s_cselect_b32 s4, s45, s5
	s_xor_b32 s47, s4, s46
	s_sub_i32 s4, s47, s46
	v_mov_b32_e32 v75, v132
	s_mul_i32 s0, s0, s15
	s_mul_i32 s5, s4, s15
	s_add_i32 s0, s0, s39
	v_ashrrev_i32_e32 v6, 3, v75
	s_sub_i32 s1, s1, s5
	v_bfe_u32 v1, v75, 6, 2
	v_xor_b32_e32 v2, v6, v75
	s_add_i32 s1, s0, s1
	s_lshl_b32 s0, s4, 7
	v_and_b32_e32 v0, 7, v75
	v_bitop3_b32 v2, v2, v1, 7 bitop3:0x6c
	v_lshrrev_b32_e32 v1, 3, v75
	v_readlane_b32 s4, v221, 5
	s_lshl_b32 s45, s1, 7
	v_bfe_u32 v77, v75, 5, 1
	v_bitop3_b32 v0, v1, v0, 3 bitop3:0x6c
	v_readlane_b32 s5, v221, 6
	v_xor_b32_e32 v7, v0, v77
	v_add_u32_e32 v3, s45, v6
	v_mov_b64_e32 v[0:1], s[4:5]
	s_movk_i32 s52, 0x1600
	v_mad_i64_i32 v[0:1], s[4:5], v3, s52, v[0:1]
	v_readlane_b32 s4, v220, 56
	v_readlane_b32 s5, v220, 57
	v_lshlrev_b32_e32 v64, 4, v2
	v_add_u32_e32 v8, s0, v6
	v_mov_b64_e32 v[2:3], s[4:5]
	v_lshlrev_b32_e32 v4, 4, v75
	v_mad_i64_i32 v[2:3], s[4:5], v8, s52, v[2:3]
	v_add_u32_e32 v78, 0, v4
	v_mov_b32_e32 v65, v96
	v_readfirstlane_b32 s4, v78
	v_add_u32_e32 v79, 0x1000, v78
	v_lshl_add_u64 v[0:1], v[0:1], 0, v[64:65]
	s_mov_b32 m0, s4
	s_mov_b64 s[72:73], 0x2c000
	v_readfirstlane_b32 s4, v79
	v_add_u32_e32 v80, 0x2000, v78
	global_load_lds_dwordx4 v[0:1], off
	v_lshl_add_u64 v[4:5], v[0:1], 0, s[72:73]
	s_mov_b32 m0, s4
	s_mov_b64 s[74:75], 0x58000
	v_readfirstlane_b32 s4, v80
	v_add_u32_e32 v81, 0x3000, v78
	global_load_lds_dwordx4 v[4:5], off
	v_lshl_add_u64 v[4:5], v[0:1], 0, s[74:75]
	s_mov_b32 m0, s4
	s_mov_b64 s[76:77], 0x84000
	v_readfirstlane_b32 s4, v81
	v_add_u32_e32 v82, 0x8000, v78
	global_load_lds_dwordx4 v[4:5], off
	v_lshl_add_u64 v[0:1], v[0:1], 0, s[76:77]
	s_mov_b32 m0, s4
	v_readfirstlane_b32 s4, v82
	v_add_u32_e32 v83, 0x9000, v78
	global_load_lds_dwordx4 v[0:1], off
	v_lshl_add_u64 v[0:1], v[2:3], 0, v[64:65]
	s_mov_b32 m0, s4
	v_readfirstlane_b32 s4, v83
	v_add_u32_e32 v84, 0xa000, v78
	global_load_lds_dwordx4 v[0:1], off
	v_lshl_add_u64 v[2:3], v[0:1], 0, s[72:73]
	s_mov_b32 m0, s4
	v_readfirstlane_b32 s4, v84
	v_add_u32_e32 v85, 0xb000, v78
	global_load_lds_dwordx4 v[2:3], off
	v_lshl_add_u64 v[2:3], v[0:1], 0, s[74:75]
	s_mov_b32 m0, s4
	v_readfirstlane_b32 s4, v85
	global_load_lds_dwordx4 v[2:3], off
	v_lshl_add_u64 v[0:1], v[0:1], 0, s[76:77]
	s_mov_b32 m0, s4
	s_mul_i32 s18, s18, 7
	global_load_lds_dwordx4 v[0:1], off
	v_and_b32_e32 v74, 31, v75
	s_add_i32 s46, s46, s18
	v_ashrrev_i32_e32 v76, 7, v75
	v_lshlrev_b32_e32 v0, 7, v74
	s_sub_i32 s4, s46, s47
	s_mul_i32 s19, s19, 7
	v_lshl_or_b32 v0, v76, 13, v0
	s_sub_i32 s4, s4, s19
	v_add_u32_e32 v86, 0, v0
	v_lshlrev_b32_e32 v0, 7, v75
	s_mul_i32 s4, s43, s4
	v_and_b32_e32 v0, 0x2f80, v0
	s_add_i32 s4, s4, s17
	s_waitcnt vmcnt(0)
	v_add_u32_e32 v87, 0, v0
	v_add_u32_e32 v2, s4, v6
	v_mov_b64_e32 v[0:1], s[70:71]
	s_waitcnt vmcnt(0)
	v_lshlrev_b32_e32 v88, 4, v7
	v_mad_i64_i32 v[66:67], s[4:5], v2, s52, v[0:1]
	v_mad_i64_i32 v[68:69], s[4:5], v8, s52, v[0:1]
	v_mov_b32_e32 v0, 0
	v_xor_b32_e32 v89, 32, v88
	v_xor_b32_e32 v90, 64, v88
	v_xor_b32_e32 v91, 0x60, v88
	s_mov_b32 s18, 0
	v_mov_b32_e32 v1, v0
	v_mov_b32_e32 v2, v0
	v_mov_b32_e32 v3, v0
	v_mov_b32_e32 v4, v0
	v_mov_b32_e32 v5, v0
	v_mov_b32_e32 v6, v0
	v_mov_b32_e32 v7, v0
	v_mov_b32_e32 v8, v0
	v_mov_b32_e32 v9, v0
	v_mov_b32_e32 v10, v0
	v_mov_b32_e32 v11, v0
	v_mov_b32_e32 v12, v0
	v_mov_b32_e32 v13, v0
	v_mov_b32_e32 v14, v0
	v_mov_b32_e32 v15, v0
	v_mov_b32_e32 v16, v0
	v_mov_b32_e32 v17, v0
	v_mov_b32_e32 v18, v0
	v_mov_b32_e32 v19, v0
	v_mov_b32_e32 v20, v0
	v_mov_b32_e32 v21, v0
	v_mov_b32_e32 v22, v0
	v_mov_b32_e32 v23, v0
	v_mov_b32_e32 v24, v0
	v_mov_b32_e32 v25, v0
	v_mov_b32_e32 v26, v0
	v_mov_b32_e32 v27, v0
	v_mov_b32_e32 v28, v0
	v_mov_b32_e32 v29, v0
	v_mov_b32_e32 v30, v0
	v_mov_b32_e32 v31, v0
	v_mov_b32_e32 v32, v0
	v_mov_b32_e32 v33, v0
	v_mov_b32_e32 v34, v0
	v_mov_b32_e32 v35, v0
	v_mov_b32_e32 v36, v0
	v_mov_b32_e32 v37, v0
	v_mov_b32_e32 v38, v0
	v_mov_b32_e32 v39, v0
	v_mov_b32_e32 v40, v0
	v_mov_b32_e32 v41, v0
	v_mov_b32_e32 v42, v0
	v_mov_b32_e32 v43, v0
	v_mov_b32_e32 v44, v0
	v_mov_b32_e32 v45, v0
	v_mov_b32_e32 v46, v0
	v_mov_b32_e32 v47, v0
	v_mov_b32_e32 v48, v0
	v_mov_b32_e32 v49, v0
	v_mov_b32_e32 v50, v0
	v_mov_b32_e32 v51, v0
	v_mov_b32_e32 v52, v0
	v_mov_b32_e32 v53, v0
	v_mov_b32_e32 v54, v0
	v_mov_b32_e32 v55, v0
	v_mov_b32_e32 v56, v0
	v_mov_b32_e32 v57, v0
	v_mov_b32_e32 v58, v0
	v_mov_b32_e32 v59, v0
	v_mov_b32_e32 v60, v0
	v_mov_b32_e32 v61, v0
	v_mov_b32_e32 v62, v0
	v_mov_b32_e32 v63, v0
	v_add_u32_e32 v92, v86, v88
	v_add_u32_e32 v93, v86, v89
	v_add_u32_e32 v94, v86, v90
	v_add_u32_e32 v95, v86, v91
	v_add_u32_e32 v97, v87, v88
	v_add_u32_e32 v98, v87, v89
	v_add_u32_e32 v99, v87, v90
	v_add_u32_e32 v100, v87, v91
	v_lshl_add_u64 v[104:105], v[66:67], 0, v[64:65]
	v_lshl_add_u64 v[106:107], v[68:69], 0, v[64:65]
	v_readfirstlane_b32 s100, v78
	s_mov_b64 s[46:47], 0x80
	s_waitcnt vmcnt(0) lgkmcnt(0)
	s_barrier
; template <int EPI, int MI>
; DI void gemm_tile(const GemmDesc& g, int tm, int tn, char* smem) {
;     ...
;   const int rowA = wm * (32 * MI) + r, rowB = wn * 64 + r;
;   const int hk = hh ^ ((r & 7) ^ ((r >> 3) & 3));
;     ...
;   G_GLDS(0, 0);
;   asm volatile("s_waitcnt vmcnt(0)" ::: "memory");
;   __syncthreads();
;   for (int kt = 0; kt < nk; kt += 2) {
;     if (kt + 1 < nk) G_GLDS(kt + 1, 1);
;     G_COMPUTE(0);
;     asm volatile("s_waitcnt vmcnt(0)" ::: "memory");
;     __syncthreads();
;     if (kt + 1 < nk) {
;       if (kt + 2 < nk) G_GLDS(kt + 2, 0);
	s_mov_b64 s[4:5], 0x5872080
	s_add_u32 m0, s100, 0x4000
	v_lshl_add_u64 v[102:103], v[104:105], 0, s[4:5]
	global_load_lds_dwordx4 v[102:103], off
	s_mov_b64 s[4:5], 0x589e080
	s_add_u32 m0, s100, 0x5000
	v_lshl_add_u64 v[102:103], v[104:105], 0, s[4:5]
	global_load_lds_dwordx4 v[102:103], off
	s_mov_b64 s[4:5], 0x58ca080
	s_add_u32 m0, s100, 0x6000
	v_lshl_add_u64 v[102:103], v[104:105], 0, s[4:5]
	global_load_lds_dwordx4 v[102:103], off
	s_mov_b64 s[4:5], 0x58f6080
	s_add_u32 m0, s100, 0x7000
	v_lshl_add_u64 v[102:103], v[104:105], 0, s[4:5]
	global_load_lds_dwordx4 v[102:103], off
	v_lshl_add_u64 v[104:105], v[104:105], 0, s[46:47]
	s_mov_b64 s[4:5], 0x1b80080
	s_add_u32 m0, s100, 0xc000
	v_lshl_add_u64 v[102:103], v[106:107], 0, s[4:5]
	global_load_lds_dwordx4 v[102:103], off
	s_mov_b64 s[4:5], 0x1bac080
	s_add_u32 m0, s100, 0xd000
	v_lshl_add_u64 v[102:103], v[106:107], 0, s[4:5]
	global_load_lds_dwordx4 v[102:103], off
	s_mov_b64 s[4:5], 0x1bd8080
	s_add_u32 m0, s100, 0xe000
	v_lshl_add_u64 v[102:103], v[106:107], 0, s[4:5]
	global_load_lds_dwordx4 v[102:103], off
	s_mov_b64 s[4:5], 0x1c04080
	s_add_u32 m0, s100, 0xf000
	v_lshl_add_u64 v[102:103], v[106:107], 0, s[4:5]
	global_load_lds_dwordx4 v[102:103], off
	v_lshl_add_u64 v[106:107], v[106:107], 0, s[46:47]
	ds_read_b128 v[240:243], v97 offset:32768
	ds_read_b128 v[244:247], v97 offset:36864
	ds_read_b128 v[224:227], v92
	ds_read_b128 v[228:231], v92 offset:4096
	s_mov_b32 s101, 0
.Lgf_loop:
	ds_read_b128 v[248:251], v98 offset:32768
	ds_read_b128 v[252:255], v98 offset:36864
	ds_read_b128 v[232:235], v93
	s_waitcnt lgkmcnt(4)
	v_mfma_f32_32x32x16_bf16 v[48:63], v[224:227], v[240:243], v[48:63]
	v_mfma_f32_32x32x16_bf16 v[32:47], v[224:227], v[244:247], v[32:47]
	ds_read_b128 v[236:239], v93 offset:4096
	s_waitcnt lgkmcnt(4)
	v_mfma_f32_32x32x16_bf16 v[16:31], v[228:231], v[240:243], v[16:31]
	v_mfma_f32_32x32x16_bf16 v[0:15], v[228:231], v[244:247], v[0:15]
	ds_read_b128 v[240:243], v99 offset:32768
	ds_read_b128 v[244:247], v99 offset:36864
	ds_read_b128 v[224:227], v94
	s_waitcnt lgkmcnt(4)
	v_mfma_f32_32x32x16_bf16 v[48:63], v[232:235], v[248:251], v[48:63]
	v_mfma_f32_32x32x16_bf16 v[32:47], v[232:235], v[252:255], v[32:47]
	ds_read_b128 v[228:231], v94 offset:4096
	s_waitcnt lgkmcnt(4)
	v_mfma_f32_32x32x16_bf16 v[16:31], v[236:239], v[248:251], v[16:31]
	v_mfma_f32_32x32x16_bf16 v[0:15], v[236:239], v[252:255], v[0:15]
	ds_read_b128 v[248:251], v100 offset:32768
	ds_read_b128 v[252:255], v100 offset:36864
	ds_read_b128 v[232:235], v95
	s_waitcnt lgkmcnt(4)
	v_mfma_f32_32x32x16_bf16 v[48:63], v[224:227], v[240:243], v[48:63]
	v_mfma_f32_32x32x16_bf16 v[32:47], v[224:227], v[244:247], v[32:47]
	ds_read_b128 v[236:239], v95 offset:4096
	s_waitcnt lgkmcnt(4)
	v_mfma_f32_32x32x16_bf16 v[16:31], v[228:231], v[240:243], v[16:31]
	v_mfma_f32_32x32x16_bf16 v[0:15], v[228:231], v[244:247], v[0:15]
	s_waitcnt lgkmcnt(0)
	s_waitcnt vmcnt(0)
	s_barrier
	s_cmp_eq_u32 s101, 42
	s_cbranch_scc1 .Lgf_noearly
	s_mov_b64 s[4:5], 0x5872080
	s_mov_b32 m0, s100
	v_lshl_add_u64 v[102:103], v[104:105], 0, s[4:5]
	global_load_lds_dwordx4 v[102:103], off
	s_mov_b64 s[4:5], 0x589e080
	s_add_u32 m0, s100, 0x1000
	v_lshl_add_u64 v[102:103], v[104:105], 0, s[4:5]
	global_load_lds_dwordx4 v[102:103], off
	s_mov_b64 s[4:5], 0x58ca080
	s_add_u32 m0, s100, 0x2000
	v_lshl_add_u64 v[102:103], v[104:105], 0, s[4:5]
	global_load_lds_dwordx4 v[102:103], off
	s_mov_b64 s[4:5], 0x58f6080
	s_add_u32 m0, s100, 0x3000
	v_lshl_add_u64 v[102:103], v[104:105], 0, s[4:5]
	global_load_lds_dwordx4 v[102:103], off
	v_lshl_add_u64 v[104:105], v[104:105], 0, s[46:47]
	s_mov_b64 s[4:5], 0x1b80080
	s_add_u32 m0, s100, 0x8000
	v_lshl_add_u64 v[102:103], v[106:107], 0, s[4:5]
	global_load_lds_dwordx4 v[102:103], off
	s_mov_b64 s[4:5], 0x1bac080
	s_add_u32 m0, s100, 0x9000
	v_lshl_add_u64 v[102:103], v[106:107], 0, s[4:5]
	global_load_lds_dwordx4 v[102:103], off
	s_mov_b64 s[4:5], 0x1bd8080
	s_add_u32 m0, s100, 0xa000
	v_lshl_add_u64 v[102:103], v[106:107], 0, s[4:5]
	global_load_lds_dwordx4 v[102:103], off
	s_mov_b64 s[4:5], 0x1c04080
	s_add_u32 m0, s100, 0xb000
	v_lshl_add_u64 v[102:103], v[106:107], 0, s[4:5]
	global_load_lds_dwordx4 v[102:103], off
	v_lshl_add_u64 v[106:107], v[106:107], 0, s[46:47]
; template <int EPI, int MI>
; DI void gemm_tile(const GemmDesc& g, int tm, int tn, char* smem) {
;     ...
;   const int rowA = wm * (32 * MI) + r, rowB = wn * 64 + r;
;   const int hk = hh ^ ((r & 7) ^ ((r >> 3) & 3));
;     ...
;   G_GLDS(0, 0);
;   asm volatile("s_waitcnt vmcnt(0)" ::: "memory");
;   __syncthreads();
;   for (int kt = 0; kt < nk; kt += 2) {
;     if (kt + 1 < nk) G_GLDS(kt + 1, 1);
;     G_COMPUTE(0);
;     asm volatile("s_waitcnt vmcnt(0)" ::: "memory");
;     __syncthreads();
;     if (kt + 1 < nk) {
;       if (kt + 2 < nk) G_GLDS(kt + 2, 0);
;       G_COMPUTE(1);
;       asm volatile("s_waitcnt vmcnt(0)" ::: "memory");
;       __syncthreads();
;     }
.Lgf_noearly:
	ds_read_b128 v[240:243], v97 offset:49152
	ds_read_b128 v[244:247], v97 offset:53248
	ds_read_b128 v[224:227], v92 offset:16384
	v_mfma_f32_32x32x16_bf16 v[48:63], v[232:235], v[248:251], v[48:63]
	v_mfma_f32_32x32x16_bf16 v[32:47], v[232:235], v[252:255], v[32:47]
	ds_read_b128 v[228:231], v92 offset:20480
	v_mfma_f32_32x32x16_bf16 v[16:31], v[236:239], v[248:251], v[16:31]
	v_mfma_f32_32x32x16_bf16 v[0:15], v[236:239], v[252:255], v[0:15]
	s_cmp_eq_u32 s101, 42
	s_cbranch_scc1 .Lgf_last
	ds_read_b128 v[248:251], v98 offset:49152
	ds_read_b128 v[252:255], v98 offset:53248
	ds_read_b128 v[232:235], v93 offset:16384
	s_waitcnt lgkmcnt(4)
	v_mfma_f32_32x32x16_bf16 v[48:63], v[224:227], v[240:243], v[48:63]
	v_mfma_f32_32x32x16_bf16 v[32:47], v[224:227], v[244:247], v[32:47]
	ds_read_b128 v[236:239], v93 offset:20480
	s_waitcnt lgkmcnt(4)
	v_mfma_f32_32x32x16_bf16 v[16:31], v[228:231], v[240:243], v[16:31]
	v_mfma_f32_32x32x16_bf16 v[0:15], v[228:231], v[244:247], v[0:15]
	ds_read_b128 v[240:243], v99 offset:49152
	ds_read_b128 v[244:247], v99 offset:53248
	ds_read_b128 v[224:227], v94 offset:16384
	s_waitcnt lgkmcnt(4)
	v_mfma_f32_32x32x16_bf16 v[48:63], v[232:235], v[248:251], v[48:63]
	v_mfma_f32_32x32x16_bf16 v[32:47], v[232:235], v[252:255], v[32:47]
	ds_read_b128 v[228:231], v94 offset:20480
	s_waitcnt lgkmcnt(4)
	v_mfma_f32_32x32x16_bf16 v[16:31], v[236:239], v[248:251], v[16:31]
	v_mfma_f32_32x32x16_bf16 v[0:15], v[236:239], v[252:255], v[0:15]
	ds_read_b128 v[248:251], v100 offset:49152
	ds_read_b128 v[252:255], v100 offset:53248
	ds_read_b128 v[232:235], v95 offset:16384
	s_waitcnt lgkmcnt(4)
	v_mfma_f32_32x32x16_bf16 v[48:63], v[224:227], v[240:243], v[48:63]
	v_mfma_f32_32x32x16_bf16 v[32:47], v[224:227], v[244:247], v[32:47]
	ds_read_b128 v[236:239], v95 offset:20480
	s_waitcnt lgkmcnt(4)
	v_mfma_f32_32x32x16_bf16 v[16:31], v[228:231], v[240:243], v[16:31]
	v_mfma_f32_32x32x16_bf16 v[0:15], v[228:231], v[244:247], v[0:15]
	s_waitcnt lgkmcnt(0)
	s_waitcnt vmcnt(0)
	s_barrier
	s_mov_b64 s[4:5], 0x5872080
	s_add_u32 m0, s100, 0x4000
	v_lshl_add_u64 v[102:103], v[104:105], 0, s[4:5]
	global_load_lds_dwordx4 v[102:103], off
	s_mov_b64 s[4:5], 0x589e080
	s_add_u32 m0, s100, 0x5000
	v_lshl_add_u64 v[102:103], v[104:105], 0, s[4:5]
	global_load_lds_dwordx4 v[102:103], off
	s_mov_b64 s[4:5], 0x58ca080
	s_add_u32 m0, s100, 0x6000
	v_lshl_add_u64 v[102:103], v[104:105], 0, s[4:5]
	global_load_lds_dwordx4 v[102:103], off
	s_mov_b64 s[4:5], 0x58f6080
	s_add_u32 m0, s100, 0x7000
	v_lshl_add_u64 v[102:103], v[104:105], 0, s[4:5]
	global_load_lds_dwordx4 v[102:103], off
	v_lshl_add_u64 v[104:105], v[104:105], 0, s[46:47]
	s_mov_b64 s[4:5], 0x1b80080
	s_add_u32 m0, s100, 0xc000
	v_lshl_add_u64 v[102:103], v[106:107], 0, s[4:5]
	global_load_lds_dwordx4 v[102:103], off
	s_mov_b64 s[4:5], 0x1bac080
	s_add_u32 m0, s100, 0xd000
	v_lshl_add_u64 v[102:103], v[106:107], 0, s[4:5]
	global_load_lds_dwordx4 v[102:103], off
	s_mov_b64 s[4:5], 0x1bd8080
	s_add_u32 m0, s100, 0xe000
	v_lshl_add_u64 v[102:103], v[106:107], 0, s[4:5]
	global_load_lds_dwordx4 v[102:103], off
	s_mov_b64 s[4:5], 0x1c04080
	s_add_u32 m0, s100, 0xf000
	v_lshl_add_u64 v[102:103], v[106:107], 0, s[4:5]
	global_load_lds_dwordx4 v[102:103], off
	v_lshl_add_u64 v[106:107], v[106:107], 0, s[46:47]
	ds_read_b128 v[240:243], v97 offset:32768
	ds_read_b128 v[244:247], v97 offset:36864
	ds_read_b128 v[224:227], v92
	v_mfma_f32_32x32x16_bf16 v[48:63], v[232:235], v[248:251], v[48:63]
	v_mfma_f32_32x32x16_bf16 v[32:47], v[232:235], v[252:255], v[32:47]
	ds_read_b128 v[228:231], v92 offset:4096
	v_mfma_f32_32x32x16_bf16 v[16:31], v[236:239], v[248:251], v[16:31]
	v_mfma_f32_32x32x16_bf16 v[0:15], v[236:239], v[252:255], v[0:15]
	s_add_u32 s101, s101, 2
	s_branch .Lgf_loop
